# C2: gmlp epilogue: hoist all gate/bias loads (20 in flight) instead of 20 serialized round trips
# speedup vs baseline: 1.0208x; 1.0061x over previous
.LBB0_257:
	v_readfirstlane_b32 s22, v140
	s_ashr_i32 s10, s22, 7
	s_ashr_i32 s11, s10, 31
	s_lshl_b64 s[20:21], s[10:11], 15
	v_and_or_b32 v80, s22, 64, v145
	v_lshl_add_u64 v[18:19], v[74:75], 0, s[20:21]
	v_lshlrev_b32_e32 v0, 8, v80
	s_waitcnt vmcnt(2)
	v_or_b32_e32 v22, 0x1000, v0
	v_mov_b32_e32 v23, v1
	s_waitcnt vmcnt(0)
	v_lshl_add_u64 v[14:15], v[18:19], 0, s[34:35]
	v_lshl_add_u64 v[2:3], v[18:19], 0, v[22:23]
	v_or_b32_e32 v26, 0x2000, v0
	v_mov_b32_e32 v27, v1
	v_lshl_add_u64 v[6:7], v[14:15], 0, v[22:23]
	v_lshl_add_u64 v[20:21], v[18:19], 0, v[0:1]
	global_load_dwordx4 v[54:57], v[2:3], off
	v_or_b32_e32 v0, 0x3000, v0
	global_load_dwordx4 v[6:9], v[6:7], off
	v_lshl_add_u64 v[2:3], v[18:19], 0, v[26:27]
	v_lshl_add_u64 v[10:11], v[14:15], 0, v[26:27]
	s_mov_b64 s[20:21], 0xc0
	v_mov_b64_e32 v[82:83], s[72:73]
	global_load_dwordx4 v[58:61], v[2:3], off
	v_lshl_add_u64 v[14:15], v[14:15], 0, v[0:1]
	global_load_dwordx4 v[10:13], v[10:11], off
	v_lshl_add_u64 v[2:3], v[18:19], 0, v[0:1]
	v_lshl_add_u64 v[30:31], v[18:19], 0, s[20:21]
	v_mad_i64_i32 v[66:67], s[20:21], v87, s64, v[82:83]
	global_load_dwordx4 v[62:65], v[2:3], off
	v_lshl_add_u64 v[66:67], v[76:77], 1, v[66:67]
	global_load_dwordx4 v[14:17], v[14:15], off
	v_lshl_add_u64 v[2:3], v[18:19], 0, 64
	s_mov_b64 s[20:21], 0x1000
	v_lshl_add_u64 v[4:5], v[2:3], 0, v[22:23]
	v_lshl_add_u64 v[96:97], v[66:67], 0, s[20:21]
	v_add_co_u32_e32 v66, vcc, s26, v66
	global_load_dwordx4 v[50:53], v[20:21], off
	global_load_dwordx4 v[38:41], v[4:5], off
	v_lshl_add_u64 v[4:5], v[2:3], 0, v[26:27]
	v_lshl_add_u64 v[2:3], v[2:3], 0, v[0:1]
	v_lshl_add_u64 v[22:23], v[30:31], 0, v[22:23]
	v_lshl_add_u64 v[26:27], v[30:31], 0, v[26:27]
	v_lshl_add_u64 v[30:31], v[30:31], 0, v[0:1]
	v_addc_co_u32_e32 v67, vcc, 0, v67, vcc
	global_load_dwordx4 v[34:37], v[20:21], off offset:64
	global_load_dwordx4 v[42:45], v[4:5], off
	global_load_dwordx4 v[46:49], v[2:3], off
	s_mul_i32 s11, s10, 0x4800
	global_load_dwordx4 v[2:5], v[20:21], off offset:128
	s_add_i32 s16, s16, s96
	global_load_dwordx4 v[18:21], v[20:21], off offset:192
	v_add_u32_e32 v87, s23, v87
	global_load_dwordx4 v[22:25], v[22:23], off
	s_nop 0
	global_load_dwordx4 v[26:29], v[26:27], off
	s_nop 0
	global_load_dwordx4 v[30:33], v[30:31], off
	s_nop 0
	global_load_dwordx4 v[66:69], v[66:67], off
	s_nop 0
	global_load_dwordx4 v[70:73], v[96:97], off offset:48
	global_load_dwordx4 v[88:91], v[96:97], off offset:32
	global_load_dwordx4 v[92:95], v[96:97], off offset:16
	s_waitcnt vmcnt(3)
	v_lshlrev_b32_e32 v150, 16, v66
	v_and_b32_e32 v149, 0xffff0000, v66
	v_lshlrev_b32_e32 v148, 16, v67
	v_and_b32_e32 v146, 0xffff0000, v67
	v_lshlrev_b32_e32 v137, 16, v68
	v_and_b32_e32 v136, 0xffff0000, v68
	v_lshlrev_b32_e32 v135, 16, v69
	v_and_b32_e32 v134, 0xffff0000, v69
	s_waitcnt vmcnt(0)
	v_lshlrev_b32_e32 v133, 16, v92
	v_and_b32_e32 v132, 0xffff0000, v92
	v_lshlrev_b32_e32 v131, 16, v93
	v_and_b32_e32 v130, 0xffff0000, v93
	v_lshlrev_b32_e32 v129, 16, v94
	v_and_b32_e32 v128, 0xffff0000, v94
	v_lshlrev_b32_e32 v127, 16, v95
	v_and_b32_e32 v126, 0xffff0000, v95
	v_lshlrev_b32_e32 v125, 16, v88
	v_and_b32_e32 v124, 0xffff0000, v88
	v_lshlrev_b32_e32 v123, 16, v89
	v_and_b32_e32 v122, 0xffff0000, v89
	v_lshlrev_b32_e32 v121, 16, v90
	v_and_b32_e32 v120, 0xffff0000, v90
	v_lshlrev_b32_e32 v119, 16, v91
	v_and_b32_e32 v118, 0xffff0000, v91
	v_lshlrev_b32_e32 v117, 16, v70
	v_and_b32_e32 v116, 0xffff0000, v70
	v_lshlrev_b32_e32 v115, 16, v71
	v_and_b32_e32 v114, 0xffff0000, v71
	v_lshlrev_b32_e32 v113, 16, v72
	v_and_b32_e32 v112, 0xffff0000, v72
	v_lshlrev_b32_e32 v111, 16, v73
	v_and_b32_e32 v110, 0xffff0000, v73
	global_load_dwordx4 v[66:69], v[96:97], off offset:112
	global_load_dwordx4 v[70:73], v[96:97], off offset:96
	global_load_dwordx4 v[88:91], v[96:97], off offset:80
	global_load_dwordx4 v[92:95], v[96:97], off offset:64
	s_waitcnt vmcnt(3)
	v_and_b32_e32 v0, 0xffff0000, v66
	s_waitcnt vmcnt(2)
	v_lshlrev_b32_e32 v81, 16, v73
	s_waitcnt vmcnt(1)
	v_lshlrev_b32_e32 v101, 16, v88
	v_and_b32_e32 v100, 0xffff0000, v88
	v_lshlrev_b32_e32 v99, 16, v89
	v_and_b32_e32 v98, 0xffff0000, v89
	v_lshlrev_b32_e32 v89, 16, v72
	v_and_b32_e32 v88, 0xffff0000, v72
	v_lshlrev_b32_e32 v72, 16, v66
	v_add_f32_e32 v66, 0, v150
	v_add_f32_e32 v66, v66, v149
	v_add_f32_e32 v66, v66, v148
	v_add_f32_e32 v66, v66, v146
	v_add_f32_e32 v66, v66, v137
	v_add_f32_e32 v66, v66, v136
	v_add_f32_e32 v66, v66, v135
	v_add_f32_e32 v66, v66, v134
	v_add_f32_e32 v66, v66, v133
	v_add_f32_e32 v66, v66, v132
	v_add_f32_e32 v66, v66, v131
	v_add_f32_e32 v66, v66, v130
	v_add_f32_e32 v66, v66, v129
	v_add_f32_e32 v66, v66, v128
	v_add_f32_e32 v66, v66, v127
	v_add_f32_e32 v66, v66, v126
	v_add_f32_e32 v66, v66, v125
	v_add_f32_e32 v66, v66, v124
	v_add_f32_e32 v66, v66, v123
	v_add_f32_e32 v66, v66, v122
	v_add_f32_e32 v66, v66, v121
	v_add_f32_e32 v66, v66, v120
	v_add_f32_e32 v66, v66, v119
	v_add_f32_e32 v66, v66, v118
	v_add_f32_e32 v66, v66, v117
	v_add_f32_e32 v66, v66, v116
	v_add_f32_e32 v66, v66, v115
	v_add_f32_e32 v66, v66, v114
	v_add_f32_e32 v66, v66, v113
	v_add_f32_e32 v66, v66, v112
	v_add_f32_e32 v66, v66, v111
	s_waitcnt vmcnt(0)
	v_lshlrev_b32_e32 v109, 16, v92
	v_add_f32_e32 v66, v66, v110
	v_and_b32_e32 v108, 0xffff0000, v92
	v_add_f32_e32 v66, v66, v109
	v_lshlrev_b32_e32 v107, 16, v93
	v_add_f32_e32 v66, v66, v108
	v_and_b32_e32 v106, 0xffff0000, v93
	v_add_f32_e32 v66, v66, v107
	v_lshlrev_b32_e32 v105, 16, v94
	v_add_f32_e32 v66, v66, v106
	v_and_b32_e32 v104, 0xffff0000, v94
	v_add_f32_e32 v66, v66, v105
	v_lshlrev_b32_e32 v103, 16, v95
	v_add_f32_e32 v66, v66, v104
	v_and_b32_e32 v102, 0xffff0000, v95
	v_add_f32_e32 v66, v66, v103
	v_add_f32_e32 v66, v66, v102
	v_add_f32_e32 v66, v66, v101
	v_add_f32_e32 v66, v66, v100
	v_add_f32_e32 v66, v66, v99
	v_lshlrev_b32_e32 v97, 16, v90
	v_add_f32_e32 v66, v66, v98
	v_and_b32_e32 v96, 0xffff0000, v90
	v_add_f32_e32 v66, v66, v97
	v_lshlrev_b32_e32 v95, 16, v91
	v_add_f32_e32 v66, v66, v96
	v_and_b32_e32 v94, 0xffff0000, v91
	v_add_f32_e32 v66, v66, v95
	v_lshlrev_b32_e32 v93, 16, v70
	v_add_f32_e32 v66, v66, v94
	v_and_b32_e32 v92, 0xffff0000, v70
	v_add_f32_e32 v66, v66, v93
	v_lshlrev_b32_e32 v91, 16, v71
	v_add_f32_e32 v66, v66, v92
	v_and_b32_e32 v90, 0xffff0000, v71
	v_add_f32_e32 v66, v66, v91
	v_add_f32_e32 v66, v66, v90
	v_add_f32_e32 v66, v66, v89
	v_add_f32_e32 v66, v66, v88
	v_and_b32_e32 v73, 0xffff0000, v73
	v_add_f32_e32 v66, v66, v81
	v_add_f32_e32 v66, v66, v73
	v_add_f32_e32 v66, v66, v72
	v_add_f32_e32 v70, v66, v0
	v_and_b32_e32 v66, 0xffff0000, v67
	v_lshlrev_b32_e32 v67, 16, v67
	v_and_b32_e32 v156, 0xffff0000, v68
	v_lshlrev_b32_e32 v157, 16, v68
	v_add_f32_e32 v68, v70, v67
	v_add_f32_e32 v68, v68, v66
	v_add_f32_e32 v68, v68, v157
	v_lshlrev_b32_e32 v153, 16, v69
	v_add_f32_e32 v68, v68, v156
	v_and_b32_e32 v152, 0xffff0000, v69
	v_add_f32_e32 v68, v68, v153
	v_add_f32_e32 v68, v68, v152
	v_fmac_f32_e32 v149, 0xbc800000, v68
	v_fmac_f32_e32 v150, 0xbc800000, v68
	v_mul_f32_e32 v69, v149, v149
	v_fmac_f32_e32 v69, v150, v150
	v_fmac_f32_e32 v148, 0xbc800000, v68
	v_fmac_f32_e32 v69, v148, v148
	v_fmac_f32_e32 v146, 0xbc800000, v68
	v_fmac_f32_e32 v69, v146, v146
	v_fmac_f32_e32 v137, 0xbc800000, v68
	v_fmac_f32_e32 v69, v137, v137
	v_fmac_f32_e32 v136, 0xbc800000, v68
	v_fmac_f32_e32 v69, v136, v136
	v_fmac_f32_e32 v135, 0xbc800000, v68
	v_fmac_f32_e32 v69, v135, v135
	v_fmac_f32_e32 v134, 0xbc800000, v68
	v_fmac_f32_e32 v69, v134, v134
	v_fmac_f32_e32 v133, 0xbc800000, v68
	v_fmac_f32_e32 v69, v133, v133
	v_fmac_f32_e32 v132, 0xbc800000, v68
	v_fmac_f32_e32 v69, v132, v132
	v_fmac_f32_e32 v131, 0xbc800000, v68
	v_fmac_f32_e32 v69, v131, v131
	v_fmac_f32_e32 v130, 0xbc800000, v68
	v_fmac_f32_e32 v69, v130, v130
	v_fmac_f32_e32 v129, 0xbc800000, v68
	v_fmac_f32_e32 v69, v129, v129
	v_fmac_f32_e32 v128, 0xbc800000, v68
	v_fmac_f32_e32 v69, v128, v128
	v_fmac_f32_e32 v127, 0xbc800000, v68
	v_fmac_f32_e32 v69, v127, v127
	v_fmac_f32_e32 v126, 0xbc800000, v68
	v_fmac_f32_e32 v69, v126, v126
	v_fmac_f32_e32 v125, 0xbc800000, v68
	v_fmac_f32_e32 v69, v125, v125
	v_fmac_f32_e32 v124, 0xbc800000, v68
	v_fmac_f32_e32 v69, v124, v124
	v_fmac_f32_e32 v123, 0xbc800000, v68
	v_fmac_f32_e32 v69, v123, v123
	v_fmac_f32_e32 v122, 0xbc800000, v68
	v_fmac_f32_e32 v69, v122, v122
	v_fmac_f32_e32 v121, 0xbc800000, v68
	v_fmac_f32_e32 v69, v121, v121
	v_fmac_f32_e32 v120, 0xbc800000, v68
	v_fmac_f32_e32 v69, v120, v120
	v_fmac_f32_e32 v119, 0xbc800000, v68
	v_fmac_f32_e32 v69, v119, v119
	v_fmac_f32_e32 v118, 0xbc800000, v68
	v_fmac_f32_e32 v69, v118, v118
	v_fmac_f32_e32 v117, 0xbc800000, v68
	v_fmac_f32_e32 v69, v117, v117
	v_fmac_f32_e32 v116, 0xbc800000, v68
	v_fmac_f32_e32 v69, v116, v116
	v_fmac_f32_e32 v115, 0xbc800000, v68
	v_fmac_f32_e32 v69, v115, v115
	v_fmac_f32_e32 v114, 0xbc800000, v68
	v_fmac_f32_e32 v69, v114, v114
	v_fmac_f32_e32 v113, 0xbc800000, v68
	v_fmac_f32_e32 v69, v113, v113
	v_fmac_f32_e32 v112, 0xbc800000, v68
	v_fmac_f32_e32 v69, v112, v112
	v_fmac_f32_e32 v111, 0xbc800000, v68
	v_fmac_f32_e32 v69, v111, v111
	v_fmac_f32_e32 v110, 0xbc800000, v68
	v_fmac_f32_e32 v69, v110, v110
	v_fmac_f32_e32 v109, 0xbc800000, v68
	v_fmac_f32_e32 v69, v109, v109
	v_fmac_f32_e32 v108, 0xbc800000, v68
	v_fmac_f32_e32 v69, v108, v108
	v_fmac_f32_e32 v107, 0xbc800000, v68
	v_fmac_f32_e32 v69, v107, v107
	v_fmac_f32_e32 v106, 0xbc800000, v68
	v_fmac_f32_e32 v69, v106, v106
	v_fmac_f32_e32 v105, 0xbc800000, v68
	v_fmac_f32_e32 v69, v105, v105
	v_fmac_f32_e32 v104, 0xbc800000, v68
	v_fmac_f32_e32 v69, v104, v104
	v_fmac_f32_e32 v103, 0xbc800000, v68
	v_fmac_f32_e32 v69, v103, v103
	v_fmac_f32_e32 v102, 0xbc800000, v68
	v_fmac_f32_e32 v69, v102, v102
	v_fmac_f32_e32 v101, 0xbc800000, v68
	v_fmac_f32_e32 v69, v101, v101
	v_fmac_f32_e32 v100, 0xbc800000, v68
	v_fmac_f32_e32 v69, v100, v100
	v_fmac_f32_e32 v99, 0xbc800000, v68
	v_fmac_f32_e32 v69, v99, v99
	v_fmac_f32_e32 v98, 0xbc800000, v68
	v_fmac_f32_e32 v69, v98, v98
	v_fmac_f32_e32 v97, 0xbc800000, v68
	v_fmac_f32_e32 v69, v97, v97
	v_fmac_f32_e32 v96, 0xbc800000, v68
	v_fmac_f32_e32 v69, v96, v96
	v_fmac_f32_e32 v95, 0xbc800000, v68
	v_fmac_f32_e32 v69, v95, v95
	v_fmac_f32_e32 v94, 0xbc800000, v68
	v_fmac_f32_e32 v69, v94, v94
	v_fmac_f32_e32 v93, 0xbc800000, v68
	v_fmac_f32_e32 v69, v93, v93
	v_fmac_f32_e32 v92, 0xbc800000, v68
	v_fmac_f32_e32 v69, v92, v92
	v_fmac_f32_e32 v91, 0xbc800000, v68
	v_fmac_f32_e32 v69, v91, v91
	v_fmac_f32_e32 v90, 0xbc800000, v68
	v_fmac_f32_e32 v69, v90, v90
	v_fmac_f32_e32 v89, 0xbc800000, v68
	v_fmac_f32_e32 v69, v89, v89
	v_fmac_f32_e32 v88, 0xbc800000, v68
	v_fmac_f32_e32 v69, v88, v88
	v_fmac_f32_e32 v81, 0xbc800000, v68
	v_fmac_f32_e32 v69, v81, v81
	v_fmac_f32_e32 v73, 0xbc800000, v68
	v_mul_f32_e32 v158, 0x3c800000, v68
	v_fmac_f32_e32 v69, v73, v73
	v_fmac_f32_e32 v72, 0xbc800000, v68
	v_fmac_f32_e32 v69, v72, v72
	v_fmac_f32_e32 v0, 0xbc800000, v68
	v_pk_add_f32 v[70:71], v[66:67], v[158:159] op_sel_hi:[1,0] neg_lo:[0,1] neg_hi:[0,1]
	v_fmac_f32_e32 v69, v0, v0
	v_pk_mul_f32 v[66:67], v[70:71], v[70:71]
	s_nop 0
	v_add_f32_e32 v67, v67, v69
	v_pk_add_f32 v[68:69], v[156:157], v[158:159] op_sel_hi:[1,0] neg_lo:[0,1] neg_hi:[0,1]
	v_add_f32_e32 v151, v66, v67
	v_pk_mul_f32 v[66:67], v[68:69], v[68:69]
	s_nop 0
	v_add_f32_e32 v67, v67, v151
	v_add_f32_e32 v151, v66, v67
	v_pk_add_f32 v[66:67], v[152:153], v[158:159] op_sel_hi:[1,0] neg_lo:[0,1] neg_hi:[0,1]
	global_load_dwordx4 v[156:159], v[78:79], off offset:16
	global_load_dwordx4 v[160:163], v[78:79], off
	v_pk_mul_f32 v[152:153], v[66:67], v[66:67]
	s_nop 0
	v_add_f32_e32 v151, v153, v151
	v_add_f32_e32 v151, v152, v151
	v_fmamk_f32 v151, v151, 0x3c800000, v177
	v_rsq_f32_e32 v151, v151
	s_nop 0
	v_mul_f32_e32 v150, v150, v151
	v_mul_f32_e32 v149, v149, v151
	v_mul_f32_e32 v148, v148, v151
	v_mul_f32_e32 v146, v146, v151
	v_mul_f32_e32 v137, v137, v151
	v_mul_f32_e32 v136, v136, v151
	v_mul_f32_e32 v135, v135, v151
	v_mul_f32_e32 v134, v134, v151
	v_mul_f32_e32 v133, v133, v151
	v_mul_f32_e32 v132, v132, v151
	v_mul_f32_e32 v131, v131, v151
	v_mul_f32_e32 v130, v130, v151
	v_mul_f32_e32 v129, v129, v151
	v_mul_f32_e32 v128, v128, v151
	v_mul_f32_e32 v127, v127, v151
	v_mul_f32_e32 v126, v126, v151
	v_mul_f32_e32 v125, v125, v151
	v_mul_f32_e32 v124, v124, v151
	v_mul_f32_e32 v123, v123, v151
	v_mul_f32_e32 v122, v122, v151
	v_mul_f32_e32 v121, v121, v151
	v_mul_f32_e32 v120, v120, v151
	v_mul_f32_e32 v119, v119, v151
	v_mul_f32_e32 v118, v118, v151
	v_mul_f32_e32 v117, v117, v151
	v_mul_f32_e32 v116, v116, v151
	v_mul_f32_e32 v115, v115, v151
	v_mul_f32_e32 v114, v114, v151
	v_mul_f32_e32 v113, v113, v151
	v_mul_f32_e32 v112, v112, v151
	v_mul_f32_e32 v111, v111, v151
	v_mul_f32_e32 v110, v110, v151
	v_mul_f32_e32 v109, v109, v151
	v_mul_f32_e32 v108, v108, v151
	v_mul_f32_e32 v107, v107, v151
	v_mul_f32_e32 v106, v106, v151
	v_mul_f32_e32 v105, v105, v151
	v_mul_f32_e32 v104, v104, v151
	v_mul_f32_e32 v103, v103, v151
	v_mul_f32_e32 v102, v102, v151
	v_mul_f32_e32 v101, v101, v151
	v_mul_f32_e32 v100, v100, v151
	v_mul_f32_e32 v99, v99, v151
	v_mul_f32_e32 v98, v98, v151
	v_mul_f32_e32 v97, v97, v151
	v_mul_f32_e32 v96, v96, v151
	v_mul_f32_e32 v95, v95, v151
	v_mul_f32_e32 v94, v94, v151
	v_mul_f32_e32 v93, v93, v151
	v_mul_f32_e32 v92, v92, v151
	v_mul_f32_e32 v91, v91, v151
	v_mul_f32_e32 v90, v90, v151
	v_mul_f32_e32 v89, v89, v151
	v_mul_f32_e32 v88, v88, v151
	v_mul_f32_e32 v81, v81, v151
	v_mul_f32_e32 v73, v73, v151
	v_mul_f32_e32 v0, v0, v151
	v_mul_f32_e32 v72, v72, v151
	v_mul_f32_e32 v70, v70, v151
	v_mul_f32_e32 v68, v68, v151
	v_mul_f32_e32 v66, v66, v151
	s_waitcnt vmcnt(1)
	v_mul_f32_e32 v137, v156, v137
	s_waitcnt vmcnt(0)
	v_mul_f32_e32 v150, v160, v150
	v_mul_f32_e32 v149, v161, v149
	v_cvt_pk_bf16_f32 v160, v150, v149
	v_mul_f32_e32 v148, v162, v148
	v_mul_f32_e32 v146, v163, v146
	v_cvt_pk_bf16_f32 v161, v148, v146
	v_mul_f32_e32 v136, v157, v136
	v_cvt_pk_bf16_f32 v162, v137, v136
	v_mul_f32_e32 v135, v158, v135
	v_mul_f32_e32 v134, v159, v134
	v_cvt_pk_bf16_f32 v163, v135, v134
	ds_write_b128 v86, v[160:163]
	global_load_dwordx4 v[134:137], v[78:79], off offset:48
	global_load_dwordx4 v[156:159], v[78:79], off offset:32
	s_waitcnt vmcnt(1)
	v_mul_f32_e32 v129, v134, v129
	s_waitcnt vmcnt(0)
	v_mul_f32_e32 v133, v156, v133
	v_mul_f32_e32 v132, v157, v132
	v_cvt_pk_bf16_f32 v132, v133, v132
	v_mul_f32_e32 v131, v158, v131
	v_mul_f32_e32 v130, v159, v130
	v_cvt_pk_bf16_f32 v133, v131, v130
	v_mul_f32_e32 v128, v135, v128
	v_cvt_pk_bf16_f32 v134, v129, v128
	v_mul_f32_e32 v127, v136, v127
	v_mul_f32_e32 v126, v137, v126
	v_cvt_pk_bf16_f32 v135, v127, v126
	ds_write_b128 v86, v[132:135] offset:16
	global_load_dwordx4 v[126:129], v[78:79], off offset:80
	global_load_dwordx4 v[130:133], v[78:79], off offset:64
	s_waitcnt vmcnt(1)
	v_mul_f32_e32 v121, v126, v121
	s_waitcnt vmcnt(0)
	v_mul_f32_e32 v125, v130, v125
	v_mul_f32_e32 v124, v131, v124
	v_cvt_pk_bf16_f32 v124, v125, v124
	v_mul_f32_e32 v123, v132, v123
	v_mul_f32_e32 v122, v133, v122
	v_cvt_pk_bf16_f32 v125, v123, v122
	v_mul_f32_e32 v120, v127, v120
	v_cvt_pk_bf16_f32 v126, v121, v120
	v_mul_f32_e32 v119, v128, v119
	v_mul_f32_e32 v118, v129, v118
	v_cvt_pk_bf16_f32 v127, v119, v118
	ds_write_b128 v86, v[124:127] offset:32
	global_load_dwordx4 v[118:121], v[78:79], off offset:112
	global_load_dwordx4 v[122:125], v[78:79], off offset:96
	s_waitcnt vmcnt(1)
	v_mul_f32_e32 v113, v118, v113
	s_waitcnt vmcnt(0)
	v_mul_f32_e32 v117, v122, v117
	v_mul_f32_e32 v116, v123, v116
	v_cvt_pk_bf16_f32 v116, v117, v116
	v_mul_f32_e32 v115, v124, v115
	v_mul_f32_e32 v114, v125, v114
	v_cvt_pk_bf16_f32 v117, v115, v114
	v_mul_f32_e32 v112, v119, v112
	v_cvt_pk_bf16_f32 v118, v113, v112
	v_mul_f32_e32 v111, v120, v111
	v_mul_f32_e32 v110, v121, v110
	v_cvt_pk_bf16_f32 v119, v111, v110
	ds_write_b128 v86, v[116:119] offset:48
	global_load_dwordx4 v[110:113], v[78:79], off offset:144
	global_load_dwordx4 v[114:117], v[78:79], off offset:128
	s_waitcnt vmcnt(1)
	v_mul_f32_e32 v105, v110, v105
	s_waitcnt vmcnt(0)
	v_mul_f32_e32 v109, v114, v109
	v_mul_f32_e32 v108, v115, v108
	v_cvt_pk_bf16_f32 v108, v109, v108
	v_mul_f32_e32 v107, v116, v107
	v_mul_f32_e32 v106, v117, v106
	v_cvt_pk_bf16_f32 v109, v107, v106
	v_mul_f32_e32 v104, v111, v104
	v_cvt_pk_bf16_f32 v110, v105, v104
	v_mul_f32_e32 v103, v112, v103
	v_mul_f32_e32 v102, v113, v102
	v_cvt_pk_bf16_f32 v111, v103, v102
	ds_write_b128 v86, v[108:111] offset:64
	global_load_dwordx4 v[102:105], v[78:79], off offset:176
	global_load_dwordx4 v[106:109], v[78:79], off offset:160
	s_waitcnt vmcnt(1)
	v_mul_f32_e32 v97, v102, v97
	s_waitcnt vmcnt(0)
	v_mul_f32_e32 v101, v106, v101
	v_mul_f32_e32 v100, v107, v100
	v_cvt_pk_bf16_f32 v100, v101, v100
	v_mul_f32_e32 v99, v108, v99
	v_mul_f32_e32 v98, v109, v98
	v_cvt_pk_bf16_f32 v101, v99, v98
	v_mul_f32_e32 v96, v103, v96
	v_cvt_pk_bf16_f32 v102, v97, v96
	v_mul_f32_e32 v95, v104, v95
	v_mul_f32_e32 v94, v105, v94
	v_cvt_pk_bf16_f32 v103, v95, v94
	ds_write_b128 v86, v[100:103] offset:80
	global_load_dwordx4 v[94:97], v[78:79], off offset:208
	global_load_dwordx4 v[98:101], v[78:79], off offset:192
	s_waitcnt vmcnt(1)
	v_mul_f32_e32 v89, v94, v89
	s_waitcnt vmcnt(0)
	v_mul_f32_e32 v93, v98, v93
	v_mul_f32_e32 v92, v99, v92
	v_cvt_pk_bf16_f32 v92, v93, v92
	v_mul_f32_e32 v91, v100, v91
	v_mul_f32_e32 v90, v101, v90
	v_cvt_pk_bf16_f32 v93, v91, v90
	v_mul_f32_e32 v88, v95, v88
	v_cvt_pk_bf16_f32 v94, v89, v88
	v_mul_f32_e32 v81, v96, v81
	v_mul_f32_e32 v73, v97, v73
	v_cvt_pk_bf16_f32 v95, v81, v73
	ds_write_b128 v86, v[92:95] offset:96
	global_load_dwordx4 v[88:91], v[78:79], off offset:240
	global_load_dwordx4 v[92:95], v[78:79], off offset:224
	v_mov_b32_e32 v81, v1
	s_waitcnt vmcnt(1)
	v_mul_f32_e32 v68, v89, v68
	s_waitcnt vmcnt(0)
	v_mul_f32_e32 v0, v93, v0
	v_mul_f32_e32 v72, v92, v72
	v_cvt_pk_bf16_f32 v92, v72, v0
	v_mul_f32_e32 v0, v71, v151
	v_mul_f32_e32 v0, v94, v0
	v_mul_f32_e32 v70, v95, v70
	v_cvt_pk_bf16_f32 v93, v0, v70
	v_mul_f32_e32 v0, v69, v151
	v_mul_f32_e32 v0, v88, v0
	v_cvt_pk_bf16_f32 v94, v0, v68
	v_mul_f32_e32 v0, v67, v151
	v_mul_f32_e32 v0, v90, v0
	v_mul_f32_e32 v66, v91, v66
	v_cvt_pk_bf16_f32 v95, v0, v66
	v_add_u32_e32 v0, s11, v84
	ds_write_b128 v86, v[92:95] offset:112
	s_waitcnt lgkmcnt(0)
	s_barrier
	ds_read_b64_tr_b16 v[68:69], v0 offset:576
	ds_read_b64_tr_b16 v[66:67], v0
	ds_read_b64_tr_b16 v[70:71], v0 offset:32
	ds_read_b64_tr_b16 v[72:73], v0 offset:608
	ds_read_b64_tr_b16 v[88:89], v0 offset:64
	ds_read_b64_tr_b16 v[90:91], v0 offset:640
	ds_read_b64_tr_b16 v[92:93], v0 offset:96
	ds_read_b64_tr_b16 v[94:95], v0 offset:672
	s_waitcnt lgkmcnt(6)
	v_mfma_f32_16x16x32_bf16 v[96:99], v[66:69], v[50:53], 0
	s_and_b32 s11, s22, 0xffffff80
	v_mfma_f32_16x16x32_bf16 v[100:103], v[66:69], v[54:57], 0
	v_mfma_f32_16x16x32_bf16 v[104:107], v[66:69], v[58:61], 0
	v_mfma_f32_16x16x32_bf16 v[66:69], v[66:69], v[62:65], 0
	s_waitcnt lgkmcnt(4)
	v_mfma_f32_16x16x32_bf16 v[108:111], v[70:73], v[50:53], 0
	v_mfma_f32_16x16x32_bf16 v[112:115], v[70:73], v[54:57], 0
	v_mfma_f32_16x16x32_bf16 v[116:119], v[70:73], v[58:61], 0
	v_mfma_f32_16x16x32_bf16 v[70:73], v[70:73], v[62:65], 0
	s_waitcnt lgkmcnt(2)
	v_mfma_f32_16x16x32_bf16 v[120:123], v[88:91], v[50:53], 0
	v_mfma_f32_16x16x32_bf16 v[124:127], v[88:91], v[54:57], 0
	v_mfma_f32_16x16x32_bf16 v[128:131], v[88:91], v[58:61], 0
	v_mfma_f32_16x16x32_bf16 v[88:91], v[88:91], v[62:65], 0
	s_waitcnt lgkmcnt(0)
	v_mfma_f32_16x16x32_bf16 v[50:53], v[92:95], v[50:53], 0
	v_mfma_f32_16x16x32_bf16 v[54:57], v[92:95], v[54:57], 0
	v_mfma_f32_16x16x32_bf16 v[58:61], v[92:95], v[58:61], 0
	v_mfma_f32_16x16x32_bf16 v[62:65], v[92:95], v[62:65], 0
	ds_read_b64_tr_b16 v[92:93], v0 offset:4608
	ds_read_b64_tr_b16 v[94:95], v0 offset:5184
	ds_read_b64_tr_b16 v[132:133], v0 offset:4640
	ds_read_b64_tr_b16 v[134:135], v0 offset:5216
	ds_read_b64_tr_b16 v[148:149], v0 offset:4672
	ds_read_b64_tr_b16 v[150:151], v0 offset:5248
	ds_read_b64_tr_b16 v[156:157], v0 offset:4704
	ds_read_b64_tr_b16 v[158:159], v0 offset:5280
	s_waitcnt lgkmcnt(6)
	v_mfma_f32_16x16x32_bf16 v[96:99], v[92:95], v[34:37], v[96:99]
	v_mfma_f32_16x16x32_bf16 v[100:103], v[92:95], v[38:41], v[100:103]
	v_mfma_f32_16x16x32_bf16 v[104:107], v[92:95], v[42:45], v[104:107]
	v_mfma_f32_16x16x32_bf16 v[66:69], v[92:95], v[46:49], v[66:69]
	s_waitcnt lgkmcnt(4)
	v_mfma_f32_16x16x32_bf16 v[92:95], v[132:135], v[34:37], v[108:111]
	v_mfma_f32_16x16x32_bf16 v[108:111], v[132:135], v[38:41], v[112:115]
	v_mfma_f32_16x16x32_bf16 v[112:115], v[132:135], v[42:45], v[116:119]
	v_mfma_f32_16x16x32_bf16 v[70:73], v[132:135], v[46:49], v[70:73]
	s_waitcnt lgkmcnt(2)
	v_mfma_f32_16x16x32_bf16 v[116:119], v[148:151], v[34:37], v[120:123]
	v_mfma_f32_16x16x32_bf16 v[120:123], v[148:151], v[38:41], v[124:127]
	v_mfma_f32_16x16x32_bf16 v[124:127], v[148:151], v[42:45], v[128:131]
	v_mfma_f32_16x16x32_bf16 v[88:91], v[148:151], v[46:49], v[88:91]
	s_waitcnt lgkmcnt(0)
	v_mfma_f32_16x16x32_bf16 v[34:37], v[156:159], v[34:37], v[50:53]
	v_mfma_f32_16x16x32_bf16 v[38:41], v[156:159], v[38:41], v[54:57]
	v_mfma_f32_16x16x32_bf16 v[42:45], v[156:159], v[42:45], v[58:61]
	v_mfma_f32_16x16x32_bf16 v[46:49], v[156:159], v[46:49], v[62:65]
	ds_read_b64_tr_b16 v[50:51], v0 offset:9216
	ds_read_b64_tr_b16 v[52:53], v0 offset:9792
	ds_read_b64_tr_b16 v[54:55], v0 offset:9248
	ds_read_b64_tr_b16 v[56:57], v0 offset:9824
	ds_read_b64_tr_b16 v[58:59], v0 offset:9280
	ds_read_b64_tr_b16 v[60:61], v0 offset:9856
	ds_read_b64_tr_b16 v[62:63], v0 offset:9312
	ds_read_b64_tr_b16 v[64:65], v0 offset:9888
	s_waitcnt lgkmcnt(6)
	v_mfma_f32_16x16x32_bf16 v[96:99], v[50:53], v[2:5], v[96:99]
	v_mfma_f32_16x16x32_bf16 v[100:103], v[50:53], v[6:9], v[100:103]
	v_mfma_f32_16x16x32_bf16 v[104:107], v[50:53], v[10:13], v[104:107]
	v_mfma_f32_16x16x32_bf16 v[50:53], v[50:53], v[14:17], v[66:69]
	s_waitcnt lgkmcnt(4)
	v_mfma_f32_16x16x32_bf16 v[66:69], v[54:57], v[2:5], v[92:95]
	v_mfma_f32_16x16x32_bf16 v[92:95], v[54:57], v[6:9], v[108:111]
	v_mfma_f32_16x16x32_bf16 v[108:111], v[54:57], v[10:13], v[112:115]
	s_waitcnt lgkmcnt(2)
	v_mfma_f32_16x16x32_bf16 v[116:119], v[58:61], v[2:5], v[116:119]
	v_mfma_f32_16x16x32_bf16 v[120:123], v[58:61], v[6:9], v[120:123]
	v_mfma_f32_16x16x32_bf16 v[124:127], v[58:61], v[10:13], v[124:127]
	v_mfma_f32_16x16x32_bf16 v[58:61], v[58:61], v[14:17], v[88:91]
	s_waitcnt lgkmcnt(0)
	v_mfma_f32_16x16x32_bf16 v[88:91], v[62:65], v[6:9], v[38:41]
	v_mfma_f32_16x16x32_bf16 v[128:131], v[62:65], v[10:13], v[42:45]
	ds_read_b64_tr_b16 v[6:7], v0 offset:13824
	ds_read_b64_tr_b16 v[8:9], v0 offset:14400
	ds_read_b64_tr_b16 v[10:11], v0 offset:13856
	ds_read_b64_tr_b16 v[12:13], v0 offset:14432
	ds_read_b64_tr_b16 v[148:149], v0 offset:13888
	ds_read_b64_tr_b16 v[150:151], v0 offset:14464
	ds_read_b64_tr_b16 v[156:157], v0 offset:13920
	ds_read_b64_tr_b16 v[158:159], v0 offset:14496
	v_mfma_f32_16x16x32_bf16 v[2:5], v[62:65], v[2:5], v[34:37]
	v_mfma_f32_16x16x32_bf16 v[112:115], v[54:57], v[14:17], v[70:73]
	v_mfma_f32_16x16x32_bf16 v[132:135], v[62:65], v[14:17], v[46:49]
	s_waitcnt lgkmcnt(6)
	v_mfma_f32_16x16x32_bf16 v[70:73], v[6:9], v[18:21], v[96:99]
	v_mfma_f32_16x16x32_bf16 v[54:57], v[6:9], v[22:25], v[100:103]
	v_mfma_f32_16x16x32_bf16 v[42:45], v[6:9], v[26:29], v[104:107]
	v_mfma_f32_16x16x32_bf16 v[14:17], v[6:9], v[30:33], v[50:53]
	s_waitcnt lgkmcnt(4)
	v_mfma_f32_16x16x32_bf16 v[66:69], v[10:13], v[18:21], v[66:69]
	v_mfma_f32_16x16x32_bf16 v[38:41], v[10:13], v[26:29], v[108:111]
	s_waitcnt lgkmcnt(2)
	v_mfma_f32_16x16x32_bf16 v[62:65], v[148:151], v[18:21], v[116:119]
	v_mfma_f32_16x16x32_bf16 v[34:37], v[148:151], v[26:29], v[124:127]
	v_mfma_f32_16x16x32_bf16 v[6:9], v[148:151], v[30:33], v[58:61]
	s_waitcnt lgkmcnt(0)
	v_mfma_f32_16x16x32_bf16 v[58:61], v[156:159], v[18:21], v[2:5]
	v_mfma_f32_16x16x32_bf16 v[18:21], v[156:159], v[26:29], v[128:131]
	v_or_b32_e32 v28, s11, v80
	v_ashrrev_i32_e32 v29, 31, v28
	v_lshl_or_b32 v26, s10, 6, v144
	v_mfma_f32_16x16x32_bf16 v[50:53], v[10:13], v[22:25], v[92:95]
	v_ashrrev_i32_e32 v27, 31, v26
	v_lshlrev_b64 v[26:27], 1, v[26:27]
	s_ashr_i32 s10, s11, 31
	v_mfma_f32_16x16x32_bf16 v[10:13], v[10:13], v[30:33], v[112:115]
	v_mfma_f32_16x16x32_bf16 v[2:5], v[156:159], v[30:33], v[132:135]
	v_mov_b32_e32 v29, s10
	v_lshl_add_u64 v[28:29], v[28:29], 2, s[50:51]
	v_mfma_f32_16x16x32_bf16 v[46:49], v[148:151], v[22:25], v[120:123]
	v_mfma_f32_16x16x32_bf16 v[22:25], v[156:159], v[22:25], v[88:91]
	v_mov_b32_e32 v195, 0
	v_lshl_add_u64 v[196:197], s[52:53], 0, v[80:81]
	v_mad_u64_u32 v[200:201], s[20:21], v196, s64, v[82:83]
	v_mov_b32_e32 v198, v201
	v_mad_u64_u32 v[198:199], s[20:21], v197, s64, v[198:199]
	v_mov_b32_e32 v201, v198
	v_lshl_add_u64 v[200:201], v[200:201], 0, v[26:27]
	v_lshlrev_b64 v[196:197], 11, v[196:197]
	v_lshl_add_u64 v[208:209], s[70:71], 0, v[196:197]
	v_lshl_add_u64 v[208:209], v[208:209], 0, v[26:27]
	global_load_dword v216, v[28:29], off
	global_load_dwordx2 v[220:221], v[200:201], off offset:3584
	global_load_dwordx2 v[222:223], v[200:201], off offset:3616
	global_load_dwordx2 v[224:225], v[200:201], off offset:3648
	global_load_dwordx2 v[226:227], v[200:201], off offset:3680
	v_or_b32_e32 v194, 16, v80
	v_lshl_add_u64 v[196:197], s[52:53], 0, v[194:195]
	v_mad_u64_u32 v[202:203], s[20:21], v196, s64, v[82:83]
	v_mov_b32_e32 v198, v203
	v_mad_u64_u32 v[198:199], s[20:21], v197, s64, v[198:199]
	v_mov_b32_e32 v203, v198
	v_lshl_add_u64 v[202:203], v[202:203], 0, v[26:27]
	v_lshlrev_b64 v[196:197], 11, v[196:197]
	v_lshl_add_u64 v[210:211], s[70:71], 0, v[196:197]
	v_lshl_add_u64 v[210:211], v[210:211], 0, v[26:27]
	global_load_dword v217, v[28:29], off offset:64
	global_load_dwordx2 v[228:229], v[202:203], off offset:3584
	global_load_dwordx2 v[230:231], v[202:203], off offset:3616
	global_load_dwordx2 v[232:233], v[202:203], off offset:3648
	global_load_dwordx2 v[234:235], v[202:203], off offset:3680
	v_or_b32_e32 v194, 32, v80
	v_lshl_add_u64 v[196:197], s[52:53], 0, v[194:195]
	v_mad_u64_u32 v[204:205], s[20:21], v196, s64, v[82:83]
	v_mov_b32_e32 v198, v205
	v_mad_u64_u32 v[198:199], s[20:21], v197, s64, v[198:199]
	v_mov_b32_e32 v205, v198
	v_lshl_add_u64 v[204:205], v[204:205], 0, v[26:27]
	v_lshlrev_b64 v[196:197], 11, v[196:197]
	v_lshl_add_u64 v[212:213], s[70:71], 0, v[196:197]
	v_lshl_add_u64 v[212:213], v[212:213], 0, v[26:27]
	global_load_dword v218, v[28:29], off offset:128
	global_load_dwordx2 v[236:237], v[204:205], off offset:3584
	global_load_dwordx2 v[238:239], v[204:205], off offset:3616
	global_load_dwordx2 v[240:241], v[204:205], off offset:3648
	global_load_dwordx2 v[242:243], v[204:205], off offset:3680
	v_or_b32_e32 v194, 48, v80
	v_lshl_add_u64 v[196:197], s[52:53], 0, v[194:195]
	v_mad_u64_u32 v[206:207], s[20:21], v196, s64, v[82:83]
	v_mov_b32_e32 v198, v207
	v_mad_u64_u32 v[198:199], s[20:21], v197, s64, v[198:199]
	v_mov_b32_e32 v207, v198
	v_lshl_add_u64 v[206:207], v[206:207], 0, v[26:27]
	v_lshlrev_b64 v[196:197], 11, v[196:197]
	v_lshl_add_u64 v[214:215], s[70:71], 0, v[196:197]
	v_lshl_add_u64 v[214:215], v[214:215], 0, v[26:27]
	global_load_dword v219, v[28:29], off offset:192
	global_load_dwordx2 v[244:245], v[206:207], off offset:3584
	global_load_dwordx2 v[246:247], v[206:207], off offset:3616
	global_load_dwordx2 v[248:249], v[206:207], off offset:3648
	global_load_dwordx2 v[250:251], v[206:207], off offset:3680
	s_add_u32 s52, s52, s24
	s_addc_u32 s53, s53, s25
	s_waitcnt vmcnt(15)
	v_add_f32_e32 v70, v70, v216
	v_add_f32_e32 v71, v71, v216
	v_add_f32_e32 v72, v72, v216
	v_add_f32_e32 v73, v73, v216
	v_lshlrev_b32_e32 v194, 16, v220
	v_and_b32_e32 v195, 0xffff0000, v220
	v_lshlrev_b32_e32 v196, 16, v221
	v_and_b32_e32 v197, 0xffff0000, v221
	v_pk_mul_f32 v[70:71], v[70:71], v[194:195]
	v_pk_mul_f32 v[72:73], v[72:73], v[196:197]
	v_cvt_pk_bf16_f32 v70, v70, v71
	v_cvt_pk_bf16_f32 v71, v72, v73
	global_store_dwordx2 v[208:209], v[70:71], off offset:1536
	v_add_f32_e32 v66, v66, v216
	v_add_f32_e32 v67, v67, v216
	v_add_f32_e32 v68, v68, v216
	v_add_f32_e32 v69, v69, v216
	v_lshlrev_b32_e32 v194, 16, v222
	v_and_b32_e32 v195, 0xffff0000, v222
	v_lshlrev_b32_e32 v196, 16, v223
	v_and_b32_e32 v197, 0xffff0000, v223
	v_pk_mul_f32 v[66:67], v[66:67], v[194:195]
	v_pk_mul_f32 v[68:69], v[68:69], v[196:197]
	v_cvt_pk_bf16_f32 v66, v66, v67
	v_cvt_pk_bf16_f32 v67, v68, v69
	global_store_dwordx2 v[208:209], v[66:67], off offset:1568
	v_add_f32_e32 v62, v62, v216
	v_add_f32_e32 v63, v63, v216
	v_add_f32_e32 v64, v64, v216
	v_add_f32_e32 v65, v65, v216
	v_lshlrev_b32_e32 v194, 16, v224
	v_and_b32_e32 v195, 0xffff0000, v224
	v_lshlrev_b32_e32 v196, 16, v225
	v_and_b32_e32 v197, 0xffff0000, v225
	v_pk_mul_f32 v[62:63], v[62:63], v[194:195]
	v_pk_mul_f32 v[64:65], v[64:65], v[196:197]
	v_cvt_pk_bf16_f32 v62, v62, v63
	v_cvt_pk_bf16_f32 v63, v64, v65
	global_store_dwordx2 v[208:209], v[62:63], off offset:1600
	v_add_f32_e32 v58, v58, v216
	v_add_f32_e32 v59, v59, v216
	v_add_f32_e32 v60, v60, v216
	v_add_f32_e32 v61, v61, v216
	v_lshlrev_b32_e32 v194, 16, v226
	v_and_b32_e32 v195, 0xffff0000, v226
	v_lshlrev_b32_e32 v196, 16, v227
	v_and_b32_e32 v197, 0xffff0000, v227
	v_pk_mul_f32 v[58:59], v[58:59], v[194:195]
	v_pk_mul_f32 v[60:61], v[60:61], v[196:197]
	v_cvt_pk_bf16_f32 v58, v58, v59
	v_cvt_pk_bf16_f32 v59, v60, v61
	global_store_dwordx2 v[208:209], v[58:59], off offset:1632
	s_waitcnt vmcnt(14)
	v_add_f32_e32 v54, v54, v217
	v_add_f32_e32 v55, v55, v217
	v_add_f32_e32 v56, v56, v217
	v_add_f32_e32 v57, v57, v217
	v_lshlrev_b32_e32 v194, 16, v228
	v_and_b32_e32 v195, 0xffff0000, v228
	v_lshlrev_b32_e32 v196, 16, v229
	v_and_b32_e32 v197, 0xffff0000, v229
	v_pk_mul_f32 v[54:55], v[54:55], v[194:195]
	v_pk_mul_f32 v[56:57], v[56:57], v[196:197]
	v_cvt_pk_bf16_f32 v54, v54, v55
	v_cvt_pk_bf16_f32 v55, v56, v57
	global_store_dwordx2 v[210:211], v[54:55], off offset:1536
	v_add_f32_e32 v50, v50, v217
	v_add_f32_e32 v51, v51, v217
	v_add_f32_e32 v52, v52, v217
	v_add_f32_e32 v53, v53, v217
	v_lshlrev_b32_e32 v194, 16, v230
	v_and_b32_e32 v195, 0xffff0000, v230
	v_lshlrev_b32_e32 v196, 16, v231
	v_and_b32_e32 v197, 0xffff0000, v231
	v_pk_mul_f32 v[50:51], v[50:51], v[194:195]
	v_pk_mul_f32 v[52:53], v[52:53], v[196:197]
	v_cvt_pk_bf16_f32 v50, v50, v51
	v_cvt_pk_bf16_f32 v51, v52, v53
	global_store_dwordx2 v[210:211], v[50:51], off offset:1568
	v_add_f32_e32 v46, v46, v217
	v_add_f32_e32 v47, v47, v217
	v_add_f32_e32 v48, v48, v217
	v_add_f32_e32 v49, v49, v217
	v_lshlrev_b32_e32 v194, 16, v232
	v_and_b32_e32 v195, 0xffff0000, v232
	v_lshlrev_b32_e32 v196, 16, v233
	v_and_b32_e32 v197, 0xffff0000, v233
	v_pk_mul_f32 v[46:47], v[46:47], v[194:195]
	v_pk_mul_f32 v[48:49], v[48:49], v[196:197]
	v_cvt_pk_bf16_f32 v46, v46, v47
	v_cvt_pk_bf16_f32 v47, v48, v49
	global_store_dwordx2 v[210:211], v[46:47], off offset:1600
	v_add_f32_e32 v22, v22, v217
	v_add_f32_e32 v23, v23, v217
	v_add_f32_e32 v24, v24, v217
	v_add_f32_e32 v25, v25, v217
	v_lshlrev_b32_e32 v194, 16, v234
	v_and_b32_e32 v195, 0xffff0000, v234
	v_lshlrev_b32_e32 v196, 16, v235
	v_and_b32_e32 v197, 0xffff0000, v235
	v_pk_mul_f32 v[22:23], v[22:23], v[194:195]
	v_pk_mul_f32 v[24:25], v[24:25], v[196:197]
	v_cvt_pk_bf16_f32 v22, v22, v23
	v_cvt_pk_bf16_f32 v23, v24, v25
	global_store_dwordx2 v[210:211], v[22:23], off offset:1632
	s_waitcnt vmcnt(13)
	v_add_f32_e32 v42, v42, v218
	v_add_f32_e32 v43, v43, v218
	v_add_f32_e32 v44, v44, v218
	v_add_f32_e32 v45, v45, v218
	v_lshlrev_b32_e32 v194, 16, v236
	v_and_b32_e32 v195, 0xffff0000, v236
	v_lshlrev_b32_e32 v196, 16, v237
	v_and_b32_e32 v197, 0xffff0000, v237
	v_pk_mul_f32 v[42:43], v[42:43], v[194:195]
	v_pk_mul_f32 v[44:45], v[44:45], v[196:197]
	v_cvt_pk_bf16_f32 v42, v42, v43
	v_cvt_pk_bf16_f32 v43, v44, v45
	global_store_dwordx2 v[212:213], v[42:43], off offset:1536
	v_add_f32_e32 v38, v38, v218
	v_add_f32_e32 v39, v39, v218
	v_add_f32_e32 v40, v40, v218
	v_add_f32_e32 v41, v41, v218
	v_lshlrev_b32_e32 v194, 16, v238
	v_and_b32_e32 v195, 0xffff0000, v238
	v_lshlrev_b32_e32 v196, 16, v239
	v_and_b32_e32 v197, 0xffff0000, v239
	v_pk_mul_f32 v[38:39], v[38:39], v[194:195]
	v_pk_mul_f32 v[40:41], v[40:41], v[196:197]
	v_cvt_pk_bf16_f32 v38, v38, v39
	v_cvt_pk_bf16_f32 v39, v40, v41
	global_store_dwordx2 v[212:213], v[38:39], off offset:1568
	v_add_f32_e32 v34, v34, v218
	v_add_f32_e32 v35, v35, v218
	v_add_f32_e32 v36, v36, v218
	v_add_f32_e32 v37, v37, v218
	v_lshlrev_b32_e32 v194, 16, v240
	v_and_b32_e32 v195, 0xffff0000, v240
	v_lshlrev_b32_e32 v196, 16, v241
	v_and_b32_e32 v197, 0xffff0000, v241
	v_pk_mul_f32 v[34:35], v[34:35], v[194:195]
	v_pk_mul_f32 v[36:37], v[36:37], v[196:197]
	v_cvt_pk_bf16_f32 v34, v34, v35
	v_cvt_pk_bf16_f32 v35, v36, v37
	global_store_dwordx2 v[212:213], v[34:35], off offset:1600
	v_add_f32_e32 v18, v18, v218
	v_add_f32_e32 v19, v19, v218
	v_add_f32_e32 v20, v20, v218
	v_add_f32_e32 v21, v21, v218
	v_lshlrev_b32_e32 v194, 16, v242
	v_and_b32_e32 v195, 0xffff0000, v242
	v_lshlrev_b32_e32 v196, 16, v243
	v_and_b32_e32 v197, 0xffff0000, v243
	v_pk_mul_f32 v[18:19], v[18:19], v[194:195]
	v_pk_mul_f32 v[20:21], v[20:21], v[196:197]
	v_cvt_pk_bf16_f32 v18, v18, v19
	v_cvt_pk_bf16_f32 v19, v20, v21
	global_store_dwordx2 v[212:213], v[18:19], off offset:1632
	s_waitcnt vmcnt(12)
	v_add_f32_e32 v14, v14, v219
	v_add_f32_e32 v15, v15, v219
	v_add_f32_e32 v16, v16, v219
	v_add_f32_e32 v17, v17, v219
	v_lshlrev_b32_e32 v194, 16, v244
	v_and_b32_e32 v195, 0xffff0000, v244
	v_lshlrev_b32_e32 v196, 16, v245
	v_and_b32_e32 v197, 0xffff0000, v245
	v_pk_mul_f32 v[14:15], v[14:15], v[194:195]
	v_pk_mul_f32 v[16:17], v[16:17], v[196:197]
	v_cvt_pk_bf16_f32 v14, v14, v15
	v_cvt_pk_bf16_f32 v15, v16, v17
	global_store_dwordx2 v[214:215], v[14:15], off offset:1536
	v_add_f32_e32 v10, v10, v219
	v_add_f32_e32 v11, v11, v219
	v_add_f32_e32 v12, v12, v219
	v_add_f32_e32 v13, v13, v219
	v_lshlrev_b32_e32 v194, 16, v246
	v_and_b32_e32 v195, 0xffff0000, v246
	v_lshlrev_b32_e32 v196, 16, v247
	v_and_b32_e32 v197, 0xffff0000, v247
	v_pk_mul_f32 v[10:11], v[10:11], v[194:195]
	v_pk_mul_f32 v[12:13], v[12:13], v[196:197]
	v_cvt_pk_bf16_f32 v10, v10, v11
	v_cvt_pk_bf16_f32 v11, v12, v13
	global_store_dwordx2 v[214:215], v[10:11], off offset:1568
	v_add_f32_e32 v6, v6, v219
	v_add_f32_e32 v7, v7, v219
	v_add_f32_e32 v8, v8, v219
	v_add_f32_e32 v9, v9, v219
	v_lshlrev_b32_e32 v194, 16, v248
	v_and_b32_e32 v195, 0xffff0000, v248
	v_lshlrev_b32_e32 v196, 16, v249
	v_and_b32_e32 v197, 0xffff0000, v249
	v_pk_mul_f32 v[6:7], v[6:7], v[194:195]
	v_pk_mul_f32 v[8:9], v[8:9], v[196:197]
	v_cvt_pk_bf16_f32 v6, v6, v7
	v_cvt_pk_bf16_f32 v7, v8, v9
	global_store_dwordx2 v[214:215], v[6:7], off offset:1600
	v_add_f32_e32 v2, v2, v219
	v_add_f32_e32 v3, v3, v219
	v_add_f32_e32 v4, v4, v219
	v_add_f32_e32 v5, v5, v219
	v_lshlrev_b32_e32 v194, 16, v250
	v_and_b32_e32 v195, 0xffff0000, v250
	v_lshlrev_b32_e32 v196, 16, v251
	v_and_b32_e32 v197, 0xffff0000, v251
	v_pk_mul_f32 v[2:3], v[2:3], v[194:195]
	v_pk_mul_f32 v[4:5], v[4:5], v[196:197]
	v_cvt_pk_bf16_f32 v2, v2, v3
	v_cvt_pk_bf16_f32 v3, v4, v5
	global_store_dwordx2 v[214:215], v[2:3], off offset:1632
	s_cmp_ge_i32 s16, s2
	s_barrier
	s_cbranch_scc0 .LBB0_257
	s_branch .LBB0_254
